# MLA attention loop: software-pipelined LDS fragment reads (V^T reads in PV rotated over 4 register sets with counted lgkmcnt; K reads for the first four key tiles prefetched into free VGPRs)
# speedup vs baseline: 1.0689x; 1.0119x over previous
; template <int DQK>
; __device__ __forceinline__ void attn_block(const AttnKV& a, const AttnW& gw, char* smem) {
;     ...
;             __builtin_amdgcn_s_setprio(1);
; #pragma unroll
;             for (int nt = 0; nt < 8; ++nt) {
;                 if (nt < 4 || hc >= 2) {
;                     st[0][nt] = (f32x4){0.f, 0.f, 0.f, 0.f}; st[1][nt] = (f32x4){0.f, 0.f, 0.f, 0.f};
; #pragma unroll
;                     for (int ks = 0; ks < KS; ++ks) {
;                         const bf16x8 kf = *(const bf16x8*)(Ks + (nt * 16 + lr) * KROWB + (ks * 4 + lq) * 16);
;                         st[0][nt] = __builtin_amdgcn_mfma_f32_16x16x32_bf16(kf, qf[0][ks], st[0][nt], 0, 0, 0);
;                         st[1][nt] = __builtin_amdgcn_mfma_f32_16x16x32_bf16(kf, qf[1][ks], st[1][nt], 0, 0, 0);
;                     }
;                 } else {
;                     st[0][nt] = (f32x4){-1e30f, -1e30f, -1e30f, -1e30f}; st[1][nt] = st[0][nt];
;                 }
;             }
.LBB0_1715:
	s_bitcmp1_b32 s8, 0
	s_cselect_b32 s21, 0xb400, 0
	s_setprio 1
	v_add_u32_e32 v82, s21, v155
	v_add_u32_e32 v149, v82, v146
	ds_read_b128 v[194:197], v149
	ds_read_b128 v[198:201], v149 offset:64
	ds_read_b128 v[202:205], v149 offset:128
	ds_read_b128 v[206:209], v149 offset:3584
	ds_read_b128 v[210:213], v149 offset:3648
	ds_read_b128 v[214:217], v149 offset:3712
	ds_read_b128 v[218:221], v149 offset:7168
	ds_read_b128 v[222:225], v149 offset:7232
	ds_read_b128 v[226:229], v149 offset:7296
	ds_read_b128 v[230:233], v149 offset:10752
	v_cmp_ne_u32_e64 s[8:9], 1, v3
	v_mov_b32_e32 v130, 0xf149f2ca
	v_mov_b32_e32 v131, 0xf149f2ca
	v_mov_b32_e32 v132, 0xf149f2ca
	v_mov_b32_e32 v133, 0xf149f2ca
	s_waitcnt lgkmcnt(7)
	v_mfma_f32_16x16x32_bf16 v[114:117], v[194:197], v[6:9], 0
	v_mfma_f32_16x16x32_bf16 v[82:85], v[194:197], v[18:21], 0
	v_mfma_f32_16x16x32_bf16 v[114:117], v[198:201], v[10:13], v[114:117]
	v_mfma_f32_16x16x32_bf16 v[82:85], v[198:201], v[22:25], v[82:85]
	v_mfma_f32_16x16x32_bf16 v[114:117], v[202:205], v[14:17], v[114:117]
	v_mfma_f32_16x16x32_bf16 v[82:85], v[202:205], v[26:29], v[82:85]
	ds_read_b128 v[194:197], v149 offset:10816
	ds_read_b128 v[198:201], v149 offset:10880
	s_waitcnt lgkmcnt(6)
	v_mfma_f32_16x16x32_bf16 v[118:121], v[206:209], v[6:9], 0
	v_mfma_f32_16x16x32_bf16 v[86:89], v[206:209], v[18:21], 0
	v_mfma_f32_16x16x32_bf16 v[118:121], v[210:213], v[10:13], v[118:121]
	v_mfma_f32_16x16x32_bf16 v[86:89], v[210:213], v[22:25], v[86:89]
	v_mfma_f32_16x16x32_bf16 v[118:121], v[214:217], v[14:17], v[118:121]
	v_mfma_f32_16x16x32_bf16 v[86:89], v[214:217], v[26:29], v[86:89]
	s_waitcnt lgkmcnt(3)
	v_mfma_f32_16x16x32_bf16 v[122:125], v[218:221], v[6:9], 0
	v_mfma_f32_16x16x32_bf16 v[90:93], v[218:221], v[18:21], 0
	v_mfma_f32_16x16x32_bf16 v[122:125], v[222:225], v[10:13], v[122:125]
	v_mfma_f32_16x16x32_bf16 v[90:93], v[222:225], v[22:25], v[90:93]
	v_mfma_f32_16x16x32_bf16 v[122:125], v[226:229], v[14:17], v[122:125]
	v_mfma_f32_16x16x32_bf16 v[90:93], v[226:229], v[26:29], v[90:93]
	s_waitcnt lgkmcnt(0)
	v_mfma_f32_16x16x32_bf16 v[126:129], v[230:233], v[6:9], 0
	v_mfma_f32_16x16x32_bf16 v[98:101], v[230:233], v[18:21], 0
	v_mfma_f32_16x16x32_bf16 v[126:129], v[194:197], v[10:13], v[126:129]
	v_mfma_f32_16x16x32_bf16 v[98:101], v[194:197], v[22:25], v[98:101]
	v_mfma_f32_16x16x32_bf16 v[126:129], v[198:201], v[14:17], v[126:129]
	v_mfma_f32_16x16x32_bf16 v[98:101], v[198:201], v[26:29], v[98:101]
	v_mov_b32_e32 v102, 0xf149f2ca
	v_mov_b32_e32 v103, 0xf149f2ca
	v_mov_b32_e32 v104, 0xf149f2ca
	s_nop 0
	v_mov_b32_e32 v94, 0xf149f2ca
	v_mov_b32_e32 v105, 0xf149f2ca
	s_and_saveexec_b64 s[16:17], s[8:9]
	s_cbranch_execz .LBB0_1717
	ds_read_b128 v[102:105], v149 offset:14336
	ds_read_b128 v[106:109], v149 offset:14400
	s_waitcnt lgkmcnt(0)
	v_mfma_f32_16x16x32_bf16 v[110:113], v[102:105], v[6:9], 0
	v_mfma_f32_16x16x32_bf16 v[102:105], v[102:105], v[18:21], 0
	v_mfma_f32_16x16x32_bf16 v[110:113], v[106:109], v[10:13], v[110:113]
	v_mfma_f32_16x16x32_bf16 v[102:105], v[106:109], v[22:25], v[102:105]
	ds_read_b128 v[106:109], v149 offset:14464
	s_waitcnt lgkmcnt(0)
	v_mfma_f32_16x16x32_bf16 v[130:133], v[106:109], v[14:17], v[110:113]
	v_mfma_f32_16x16x32_bf16 v[102:105], v[106:109], v[26:29], v[102:105]

; template <int DQK>
; __device__ __forceinline__ void attn_block(const AttnKV& a, const AttnW& gw, char* smem) {
;     ...
;             __builtin_amdgcn_s_setprio(1);
; #pragma unroll
;             for (int k2 = 0; k2 < 4; ++k2) {
;                 if (k2 < 2 || hc >= 2) {
;                     bf16x8 pf[2];
; #pragma unroll
;                     for (int qt = 0; qt < 2; ++qt) {
;                         const f32x8 p8 = __builtin_shufflevector(st[qt][2 * k2], st[qt][2 * k2 + 1], 0, 1, 2, 3, 4, 5, 6, 7);
;                         pf[qt] = __builtin_bit_cast(bf16x8, __builtin_convertvector(p8, bf16v8_t));
;                     }
; #pragma unroll
;                     for (int dt = 0; dt < 4; ++dt) {
;                         const char* vrow = Vs + (dt * 16 + lr) * VROWB + lq * 8;
;                         const uint2 v0 = *(const uint2*)(vrow + (2 * k2) * 32), v1 = *(const uint2*)(vrow + (2 * k2 + 1) * 32);
;                         u32x4 vw; vw.x = v0.x; vw.y = v0.y; vw.z = v1.x; vw.w = v1.y;
;                         const bf16x8 vf = __builtin_bit_cast(bf16x8, vw);
;                         ot[0][dt] = __builtin_amdgcn_mfma_f32_16x16x32_bf16(vf, pf[0], ot[0][dt], 0, 0, 0);
;                         ot[1][dt] = __builtin_amdgcn_mfma_f32_16x16x32_bf16(vf, pf[1], ot[1][dt], 0, 0, 0);
;                     }
;                 }
;             }
;             __builtin_amdgcn_s_setprio(0);
.LBB0_1727:
	s_setprio 1
	v_add_u32_e32 v103, s21, v189
	v_add_u32_e32 v106, v103, v162
	v_add_u32_e32 v105, 0x7000, v106
	v_add_u32_e32 v103, 0x8000, v106
	v_add_u32_e32 v104, 0x9000, v106
	v_add_u32_e32 v106, 0xa000, v106
	v_cvt_pk_bf16_f32 v108, v178, v179
	v_cvt_pk_bf16_f32 v179, v142, v143
	v_cvt_pk_bf16_f32 v178, v140, v141
	ds_read2_b64 v[140:143], v105 offset1:4
	ds_read2_b64 v[194:197], v103 offset0:32 offset1:36
	ds_read2_b64 v[198:201], v104 offset0:64 offset1:68
	v_cvt_pk_bf16_f32 v111, v184, v185
	v_cvt_pk_bf16_f32 v110, v182, v183
	v_cvt_pk_bf16_f32 v109, v180, v181
	v_cvt_pk_bf16_f32 v181, v186, v187
	v_cvt_pk_bf16_f32 v180, v144, v145
	ds_read2_b64 v[202:205], v106 offset0:96 offset1:100
	s_waitcnt lgkmcnt(3)
	v_mfma_f32_16x16x32_bf16 v[78:81], v[140:143], v[108:111], v[78:81]
	v_cvt_pk_bf16_f32 v139, v138, v139
	v_mfma_f32_16x16x32_bf16 v[62:65], v[140:143], v[178:181], v[62:65]
	ds_read2_b64 v[140:143], v105 offset0:8 offset1:12
	v_cvt_pk_bf16_f32 v138, v100, v101
	v_cvt_pk_bf16_f32 v137, v136, v137
	s_waitcnt lgkmcnt(3)
	v_mfma_f32_16x16x32_bf16 v[74:77], v[194:197], v[108:111], v[74:77]
	v_cvt_pk_bf16_f32 v136, v134, v135
	v_mfma_f32_16x16x32_bf16 v[58:61], v[194:197], v[178:181], v[58:61]
	ds_read2_b64 v[194:197], v103 offset0:40 offset1:44
	s_waitcnt lgkmcnt(3)
	v_mfma_f32_16x16x32_bf16 v[70:73], v[198:201], v[108:111], v[70:73]
	v_mfma_f32_16x16x32_bf16 v[54:57], v[198:201], v[178:181], v[54:57]
	ds_read2_b64 v[198:201], v104 offset0:72 offset1:76
	s_waitcnt lgkmcnt(3)
	v_mfma_f32_16x16x32_bf16 v[66:69], v[202:205], v[108:111], v[66:69]
	v_cvt_pk_bf16_f32 v111, v176, v177
	v_cvt_pk_bf16_f32 v110, v174, v175
	v_cvt_pk_bf16_f32 v109, v172, v173
	v_mfma_f32_16x16x32_bf16 v[50:53], v[202:205], v[178:181], v[50:53]
	ds_read2_b64 v[202:205], v106 offset0:104 offset1:108
	v_cvt_pk_bf16_f32 v108, v170, v171
	s_waitcnt lgkmcnt(3)
	v_mfma_f32_16x16x32_bf16 v[62:65], v[140:143], v[136:139], v[62:65]
	v_mfma_f32_16x16x32_bf16 v[78:81], v[140:143], v[108:111], v[78:81]
	s_waitcnt lgkmcnt(2)
	v_mfma_f32_16x16x32_bf16 v[74:77], v[194:197], v[108:111], v[74:77]
	v_mfma_f32_16x16x32_bf16 v[58:61], v[194:197], v[136:139], v[58:61]
	s_waitcnt lgkmcnt(1)
	v_mfma_f32_16x16x32_bf16 v[70:73], v[198:201], v[108:111], v[70:73]
	v_mfma_f32_16x16x32_bf16 v[54:57], v[198:201], v[136:139], v[54:57]
	s_waitcnt lgkmcnt(0)
	v_mfma_f32_16x16x32_bf16 v[66:69], v[202:205], v[108:111], v[66:69]
	v_mfma_f32_16x16x32_bf16 v[50:53], v[202:205], v[136:139], v[50:53]
	s_and_saveexec_b64 s[16:17], s[8:9]
	s_cbranch_execz .LBB0_1729
	v_cvt_pk_bf16_f32 v97, v96, v97
	v_cvt_pk_bf16_f32 v96, v94, v95
	v_cvt_pk_bf16_f32 v95, v98, v99
	ds_read2_b64 v[98:101], v105 offset0:16 offset1:20
	ds_read2_b64 v[194:197], v103 offset0:48 offset1:52
	ds_read2_b64 v[198:201], v104 offset0:80 offset1:84
	ds_read2_b64 v[202:205], v106 offset0:112 offset1:116
	v_cvt_pk_bf16_f32 v111, v132, v133
	v_cvt_pk_bf16_f32 v110, v130, v131
	v_cvt_pk_bf16_f32 v109, v128, v129
	v_cvt_pk_bf16_f32 v108, v126, v127
	v_cvt_pk_bf16_f32 v94, v92, v93
	v_cvt_pk_bf16_f32 v91, v90, v91
	s_waitcnt lgkmcnt(3)
	v_mfma_f32_16x16x32_bf16 v[78:81], v[98:101], v[108:111], v[78:81]
	v_cvt_pk_bf16_f32 v90, v88, v89
	v_cvt_pk_bf16_f32 v89, v86, v87
	v_cvt_pk_bf16_f32 v88, v84, v85
	v_mfma_f32_16x16x32_bf16 v[62:65], v[98:101], v[94:97], v[62:65]
	ds_read2_b64 v[84:87], v105 offset0:24 offset1:28
	v_cvt_pk_bf16_f32 v93, v120, v121
	s_waitcnt lgkmcnt(3)
	v_mfma_f32_16x16x32_bf16 v[74:77], v[194:197], v[108:111], v[74:77]
	v_cvt_pk_bf16_f32 v92, v118, v119
	v_mfma_f32_16x16x32_bf16 v[58:61], v[194:197], v[94:97], v[58:61]
	ds_read2_b64 v[140:143], v103 offset0:56 offset1:60
	s_waitcnt lgkmcnt(3)
	v_mfma_f32_16x16x32_bf16 v[70:73], v[198:201], v[108:111], v[70:73]
	v_mfma_f32_16x16x32_bf16 v[54:57], v[198:201], v[94:97], v[54:57]
	ds_read2_b64 v[194:197], v104 offset0:88 offset1:92
	s_waitcnt lgkmcnt(3)
	v_mfma_f32_16x16x32_bf16 v[50:53], v[202:205], v[94:97], v[50:53]
	v_cvt_pk_bf16_f32 v95, v124, v125
	v_cvt_pk_bf16_f32 v94, v122, v123
	ds_read2_b64 v[198:201], v106 offset0:120 offset1:124
	s_waitcnt lgkmcnt(3)
	v_mfma_f32_16x16x32_bf16 v[62:65], v[84:87], v[88:91], v[62:65]
	s_nop 0
	v_mfma_f32_16x16x32_bf16 v[78:81], v[84:87], v[92:95], v[78:81]
	s_waitcnt lgkmcnt(2)
	v_mfma_f32_16x16x32_bf16 v[74:77], v[140:143], v[92:95], v[74:77]
	v_mfma_f32_16x16x32_bf16 v[58:61], v[140:143], v[88:91], v[58:61]
	s_waitcnt lgkmcnt(1)
	v_mfma_f32_16x16x32_bf16 v[70:73], v[194:197], v[92:95], v[70:73]
	v_mfma_f32_16x16x32_bf16 v[54:57], v[194:197], v[88:91], v[54:57]
	v_mfma_f32_16x16x32_bf16 v[66:69], v[202:205], v[108:111], v[66:69]
	s_waitcnt lgkmcnt(0)
	v_mfma_f32_16x16x32_bf16 v[66:69], v[198:201], v[92:95], v[66:69]
	v_mfma_f32_16x16x32_bf16 v[50:53], v[198:201], v[88:91], v[50:53]
